# v53 + out-proj epilogue: residual address calc and the 16 first-batch residual loads hoisted above the stagger re-sync barrier
# baseline (speedup 1.0000x reference)
; #define PG8_STAGE(bufoff, gbase, voff) do { _Pragma("unroll") for (int _i = 0; _i < 2; ++_i) \
;         __builtin_amdgcn_global_load_lds((const unsigned*)((const char*)(gbase) + (voff)[_i]), (LAS unsigned*)(lds + (bufoff) + ldsw + _i * 8192), 16, 0, 0); } while (0)
; #define PG8_LDA(dst, b, h) do { _Pragma("unroll") for (int m = 0; m < 4; ++m) _Pragma("unroll") for (int k = 0; k < 2; ++k) dst[m][k] = *(const LAS bf16x8*)(lds + PG8_SA(b, h) + aoff + m * 2048 + k * 1024); } while (0)
; #define PG8_LDB(dst, b, h) do { _Pragma("unroll") for (int n = 0; n < 2; ++n) _Pragma("unroll") for (int k = 0; k < 2; ++k) dst[n][k] = *(const LAS bf16x8*)(lds + PG8_SB(b, h) + boff + n * 2048 + k * 1024); } while (0)
; #define PG8_MMA(ai, bj, At, Bt) do { __builtin_amdgcn_s_setprio(1); _Pragma("unroll") for (int m = 0; m < 4; ++m) _Pragma("unroll") for (int n = 0; n < 2; ++n) _Pragma("unroll") for (int k = 0; k < 2; ++k) \
;         acc[ai][bj][m][n] = __builtin_amdgcn_mfma_f32_16x16x32_bf16(Bt[n][k], At[m][k], acc[ai][bj][m][n], 0, 0, 0); __builtin_amdgcn_s_setprio(0); } while (0)
; #define PG8_WAIT_V(n) asm volatile("s_waitcnt vmcnt(" #n ")" ::: "memory")
; #define PG8_WAIT_L(n) asm volatile("s_waitcnt lgkmcnt(" #n ")" ::: "memory")
; #define PG8_BAR __builtin_amdgcn_s_barrier()
; template <class Epi>
; __device__ __forceinline__ void gemm_phase(LAS unsigned char* lds, const Gemm g, const StaticOrder& S, const Epi& E, const int tid) {
;     ...
;         for (int t = 0; t < nt; t += 2) {
;             const bool last = (t == nt - 2);
;             const char* a1 = cA + (size_t)(t + 1) * kstep + ((t + 1) >= 8 ? xtra : 0);
;             const char* a2 = last ? nA : cA + (size_t)(t + 2) * kstep + ((t + 2) >= 8 ? xtra : 0); const char* b2 = last ? nB : cB + (size_t)(t + 2) * kstep;
;             const char* a3 = a2 + kstep; const char* b3 = b2 + kstep;
;             PG8_LDB(B0, 0, 0); PG8_LDB(B1, 0, 1); PG8_SCHED; PG8_LDA(At, 0, 0); PG8_STAGE(PG8_SA(1, 1), a1 + hstepA, voffA);
;             PG8_WAIT_V(8); PG8_WAIT_L(0); PG8_BAR; PG8_MMA(0, 0, At, B0); PG8_MMA(0, 1, At, B1); PG8_BAR; PG8_SCHED;
;             PG8_LDA(At, 0, 1); PG8_STAGE(PG8_SB(0, 0), b2, voffB); PG8_STAGE(PG8_SB(0, 1), b2 + hstepB, voffB); PG8_STAGE(PG8_SA(0, 0), a2, voffA);
;             PG8_WAIT_V(8); PG8_WAIT_L(0); PG8_BAR; PG8_MMA(1, 0, At, B0); PG8_MMA(1, 1, At, B1); PG8_BAR; PG8_SCHED;
.LBB0_160:
	s_add_u32 s42, s94, 0x100
	s_addc_u32 s43, s95, 0
	s_add_i32 s8, 0, 0x10000
	v_add_u32_e32 v142, s8, v245
	v_add_u32_e32 v158, s15, v245
	ds_read_b128 v[122:125], v142
	ds_read_b128 v[126:129], v142 offset:1024
	ds_read_b128 v[138:141], v142 offset:2048
	ds_read_b128 v[142:145], v142 offset:3072
	ds_read_b128 v[146:149], v158
	ds_read_b128 v[150:153], v158 offset:1024
	ds_read_b128 v[154:157], v158 offset:2048
	ds_read_b128 v[158:161], v158 offset:3072
	s_cmp_eq_u32 s89, 12
	s_cselect_b32 vcc_hi, s91, s43
	s_cselect_b32 vcc_lo, s90, s42
	s_cselect_b32 s93, s36, s46
	s_cselect_b32 s92, s37, s45
	v_lshl_add_u64 v[210:211], s[94:95], 0, v[206:207]
	s_add_i32 m0, s19, 0xc000
	ds_read_b128 v[162:165], v246
	ds_read_b128 v[166:169], v246 offset:1024
	ds_read_b128 v[170:173], v246 offset:2048
	ds_read_b128 v[174:177], v246 offset:3072
	ds_read_b128 v[178:181], v246 offset:4096
	ds_read_b128 v[182:185], v246 offset:5120
	ds_read_b128 v[186:189], v246 offset:6144
	ds_read_b128 v[190:193], v246 offset:7168
	global_load_lds_dwordx4 v[210:211], off
	v_lshl_add_u64 v[210:211], s[94:95], 0, v[208:209]
	s_add_i32 m0, s19, 0xe000
	s_nop 0
	global_load_lds_dwordx4 v[210:211], off
	s_waitcnt vmcnt(8)
	s_waitcnt lgkmcnt(0)
	s_barrier
	s_setprio 1
	s_waitcnt lgkmcnt(0)
	v_mfma_f32_16x16x32_bf16 v[134:137], v[122:125], v[162:165], v[134:137]
	v_mfma_f32_16x16x32_bf16 v[130:133], v[138:141], v[162:165], v[130:133]
	v_mfma_f32_16x16x32_bf16 v[108:111], v[122:125], v[170:173], v[108:111]
	v_mfma_f32_16x16x32_bf16 v[104:107], v[138:141], v[170:173], v[104:107]
	v_mfma_f32_16x16x32_bf16 v[92:95], v[122:125], v[178:181], v[92:95]
	v_mfma_f32_16x16x32_bf16 v[88:91], v[138:141], v[178:181], v[88:91]
	v_mfma_f32_16x16x32_bf16 v[76:79], v[122:125], v[186:189], v[76:79]
	v_mfma_f32_16x16x32_bf16 v[72:75], v[138:141], v[186:189], v[72:75]
	v_mfma_f32_16x16x32_bf16 v[134:137], v[126:129], v[166:169], v[134:137]
	v_mfma_f32_16x16x32_bf16 v[130:133], v[142:145], v[166:169], v[130:133]
	v_mfma_f32_16x16x32_bf16 v[108:111], v[126:129], v[174:177], v[108:111]
	v_mfma_f32_16x16x32_bf16 v[104:107], v[142:145], v[174:177], v[104:107]
	v_mfma_f32_16x16x32_bf16 v[92:95], v[126:129], v[182:185], v[92:95]
	v_mfma_f32_16x16x32_bf16 v[88:91], v[142:145], v[182:185], v[88:91]
	v_mfma_f32_16x16x32_bf16 v[76:79], v[126:129], v[190:193], v[76:79]
	v_mfma_f32_16x16x32_bf16 v[72:75], v[142:145], v[190:193], v[72:75]
	v_mfma_f32_16x16x32_bf16 v[118:121], v[146:149], v[162:165], v[118:121]
	v_mfma_f32_16x16x32_bf16 v[114:117], v[154:157], v[162:165], v[114:117]
	v_mfma_f32_16x16x32_bf16 v[100:103], v[146:149], v[170:173], v[100:103]
	v_mfma_f32_16x16x32_bf16 v[96:99], v[154:157], v[170:173], v[96:99]
	v_mfma_f32_16x16x32_bf16 v[84:87], v[146:149], v[178:181], v[84:87]
	v_mfma_f32_16x16x32_bf16 v[80:83], v[154:157], v[178:181], v[80:83]
	v_mfma_f32_16x16x32_bf16 v[68:71], v[146:149], v[186:189], v[68:71]
	v_mfma_f32_16x16x32_bf16 v[64:67], v[154:157], v[186:189], v[64:67]
	v_mfma_f32_16x16x32_bf16 v[118:121], v[150:153], v[166:169], v[118:121]
	v_mfma_f32_16x16x32_bf16 v[114:117], v[158:161], v[166:169], v[114:117]
	v_mfma_f32_16x16x32_bf16 v[100:103], v[150:153], v[174:177], v[100:103]
	v_mfma_f32_16x16x32_bf16 v[96:99], v[158:161], v[174:177], v[96:99]
	v_mfma_f32_16x16x32_bf16 v[84:87], v[150:153], v[182:185], v[84:87]
	v_mfma_f32_16x16x32_bf16 v[80:83], v[158:161], v[182:185], v[80:83]
	v_mfma_f32_16x16x32_bf16 v[68:71], v[150:153], v[190:193], v[68:71]
	v_mfma_f32_16x16x32_bf16 v[64:67], v[158:161], v[190:193], v[64:67]
	s_setprio 0
	s_barrier
	s_add_i32 s8, s8, s11
	v_lshl_add_u64 v[210:211], s[92:93], 0, v[112:113]
	s_mov_b32 m0, s8
	ds_read_b128 v[162:165], v246 offset:16384
	ds_read_b128 v[166:169], v246 offset:17408
	ds_read_b128 v[170:173], v246 offset:18432
	ds_read_b128 v[174:177], v246 offset:19456
	ds_read_b128 v[178:181], v246 offset:20480
	ds_read_b128 v[182:185], v246 offset:21504
	ds_read_b128 v[186:189], v246 offset:22528
	ds_read_b128 v[190:193], v246 offset:23552
	global_load_lds_dwordx4 v112, s[92:93]
	s_add_i32 m0, s8, 0x2000
	s_add_u32 s8, s92, 0x40000
	v_lshl_add_u64 v[212:213], s[92:93], 0, v[200:201]
	s_addc_u32 s9, s93, 0
	s_add_i32 s13, s15, s11
	global_load_lds_dwordx4 v200, s[92:93]
	s_nop 0
	s_mov_b32 m0, s13
	s_nop 0
	global_load_lds_dwordx4 v112, s[8:9]
	s_nop 0
	s_add_i32 m0, s13, 0x2000
	s_nop 0
	global_load_lds_dwordx4 v200, s[8:9]
	s_nop 0
	s_mov_b32 m0, s19
	s_nop 0
	global_load_lds_dwordx4 v202, vcc
	s_mov_b32 m0, s28
	s_nop 0
	global_load_lds_dwordx4 v204, vcc
	s_waitcnt vmcnt(8)
	s_waitcnt lgkmcnt(0)
	s_barrier
; #define PG8_STAGE(bufoff, gbase, voff) do { _Pragma("unroll") for (int _i = 0; _i < 2; ++_i) \
;         __builtin_amdgcn_global_load_lds((const unsigned*)((const char*)(gbase) + (voff)[_i]), (LAS unsigned*)(lds + (bufoff) + ldsw + _i * 8192), 16, 0, 0); } while (0)
; #define PG8_LDA(dst, b, h) do { _Pragma("unroll") for (int m = 0; m < 4; ++m) _Pragma("unroll") for (int k = 0; k < 2; ++k) dst[m][k] = *(const LAS bf16x8*)(lds + PG8_SA(b, h) + aoff + m * 2048 + k * 1024); } while (0)
; #define PG8_LDB(dst, b, h) do { _Pragma("unroll") for (int n = 0; n < 2; ++n) _Pragma("unroll") for (int k = 0; k < 2; ++k) dst[n][k] = *(const LAS bf16x8*)(lds + PG8_SB(b, h) + boff + n * 2048 + k * 1024); } while (0)
; #define PG8_MMA(ai, bj, At, Bt) do { __builtin_amdgcn_s_setprio(1); _Pragma("unroll") for (int m = 0; m < 4; ++m) _Pragma("unroll") for (int n = 0; n < 2; ++n) _Pragma("unroll") for (int k = 0; k < 2; ++k) \
;         acc[ai][bj][m][n] = __builtin_amdgcn_mfma_f32_16x16x32_bf16(Bt[n][k], At[m][k], acc[ai][bj][m][n], 0, 0, 0); __builtin_amdgcn_s_setprio(0); } while (0)
; #define PG8_WAIT_V(n) asm volatile("s_waitcnt vmcnt(" #n ")" ::: "memory")
; #define PG8_WAIT_L(n) asm volatile("s_waitcnt lgkmcnt(" #n ")" ::: "memory")
; #define PG8_BAR __builtin_amdgcn_s_barrier()
; #define PG8_SCHED __builtin_amdgcn_sched_barrier(0)
; template <class Epi>
; __device__ __forceinline__ void gemm_phase(LAS unsigned char* lds, const Gemm g, const StaticOrder& S, const Epi& E, const int tid) {
;     ...
;             PG8_WAIT_V(8); PG8_WAIT_L(0); PG8_BAR; PG8_MMA(0, 0, At, B0); PG8_MMA(0, 1, At, B1); PG8_BAR; PG8_SCHED;
;             PG8_LDA(At, 0, 1); PG8_STAGE(PG8_SB(0, 0), b2, voffB); PG8_STAGE(PG8_SB(0, 1), b2 + hstepB, voffB); PG8_STAGE(PG8_SA(0, 0), a2, voffA);
;             PG8_WAIT_V(8); PG8_WAIT_L(0); PG8_BAR; PG8_MMA(1, 0, At, B0); PG8_MMA(1, 1, At, B1); PG8_BAR; PG8_SCHED;
;             PG8_LDB(B0, 1, 0); PG8_LDB(B1, 1, 1); PG8_SCHED; PG8_LDA(At, 1, 0); PG8_STAGE(PG8_SA(0, 1), a2 + hstepA, voffA);
;             PG8_WAIT_V(8); PG8_WAIT_L(0); PG8_BAR; PG8_MMA(0, 0, At, B0); PG8_MMA(0, 1, At, B1); PG8_BAR; PG8_SCHED;
;             PG8_LDA(At, 1, 1); PG8_STAGE(PG8_SB(1, 0), b3, voffB); PG8_STAGE(PG8_SB(1, 1), b3 + hstepB, voffB); PG8_STAGE(PG8_SA(1, 0), a3, voffA);
	s_setprio 1
	s_waitcnt lgkmcnt(0)
	v_mfma_f32_16x16x32_bf16 v[60:63], v[122:125], v[162:165], v[60:63]
	v_mfma_f32_16x16x32_bf16 v[56:59], v[138:141], v[162:165], v[56:59]
	v_mfma_f32_16x16x32_bf16 v[44:47], v[122:125], v[170:173], v[44:47]
	v_mfma_f32_16x16x32_bf16 v[40:43], v[138:141], v[170:173], v[40:43]
	v_mfma_f32_16x16x32_bf16 v[28:31], v[122:125], v[178:181], v[28:31]
	v_mfma_f32_16x16x32_bf16 v[24:27], v[138:141], v[178:181], v[24:27]
	v_mfma_f32_16x16x32_bf16 v[12:15], v[122:125], v[186:189], v[12:15]
	v_mfma_f32_16x16x32_bf16 v[8:11], v[138:141], v[186:189], v[8:11]
	v_mfma_f32_16x16x32_bf16 v[60:63], v[126:129], v[166:169], v[60:63]
	v_mfma_f32_16x16x32_bf16 v[56:59], v[142:145], v[166:169], v[56:59]
	v_mfma_f32_16x16x32_bf16 v[44:47], v[126:129], v[174:177], v[44:47]
	v_mfma_f32_16x16x32_bf16 v[40:43], v[142:145], v[174:177], v[40:43]
	v_mfma_f32_16x16x32_bf16 v[28:31], v[126:129], v[182:185], v[28:31]
	v_mfma_f32_16x16x32_bf16 v[24:27], v[142:145], v[182:185], v[24:27]
	v_mfma_f32_16x16x32_bf16 v[12:15], v[126:129], v[190:193], v[12:15]
	v_mfma_f32_16x16x32_bf16 v[8:11], v[142:145], v[190:193], v[8:11]
	v_mfma_f32_16x16x32_bf16 v[52:55], v[146:149], v[162:165], v[52:55]
	v_mfma_f32_16x16x32_bf16 v[48:51], v[154:157], v[162:165], v[48:51]
	v_mfma_f32_16x16x32_bf16 v[36:39], v[146:149], v[170:173], v[36:39]
	v_mfma_f32_16x16x32_bf16 v[32:35], v[154:157], v[170:173], v[32:35]
	v_mfma_f32_16x16x32_bf16 v[20:23], v[146:149], v[178:181], v[20:23]
	v_mfma_f32_16x16x32_bf16 v[16:19], v[154:157], v[178:181], v[16:19]
	v_mfma_f32_16x16x32_bf16 v[4:7], v[146:149], v[186:189], v[4:7]
	v_mfma_f32_16x16x32_bf16 v[0:3], v[154:157], v[186:189], v[0:3]
	v_mfma_f32_16x16x32_bf16 v[52:55], v[150:153], v[166:169], v[52:55]
	v_mfma_f32_16x16x32_bf16 v[48:51], v[158:161], v[166:169], v[48:51]
	v_mfma_f32_16x16x32_bf16 v[36:39], v[150:153], v[174:177], v[36:39]
	v_mfma_f32_16x16x32_bf16 v[32:35], v[158:161], v[174:177], v[32:35]
	v_mfma_f32_16x16x32_bf16 v[20:23], v[150:153], v[182:185], v[20:23]
	v_mfma_f32_16x16x32_bf16 v[16:19], v[158:161], v[182:185], v[16:19]
	v_mfma_f32_16x16x32_bf16 v[4:7], v[150:153], v[190:193], v[4:7]
	v_mfma_f32_16x16x32_bf16 v[0:3], v[158:161], v[190:193], v[0:3]
	s_setprio 0
	s_barrier
	s_add_i32 s13, 0, 0x18000
	s_add_i32 s31, 0, 0x1c000
	v_add_u32_e32 v142, s13, v245
	v_add_u32_e32 v158, s31, v245
	ds_read_b128 v[122:125], v142
	ds_read_b128 v[126:129], v142 offset:1024
	ds_read_b128 v[138:141], v142 offset:2048
	ds_read_b128 v[142:145], v142 offset:3072
	ds_read_b128 v[146:149], v158
	ds_read_b128 v[150:153], v158 offset:1024
	ds_read_b128 v[154:157], v158 offset:2048
	ds_read_b128 v[158:161], v158 offset:3072
	s_add_u32 s8, vcc_lo, 0xc0000
	s_addc_u32 s9, vcc_hi, 0
	s_mov_b32 m0, s30
	s_nop 0
	ds_read_b128 v[162:165], v246 offset:32768
	ds_read_b128 v[166:169], v246 offset:33792
	ds_read_b128 v[170:173], v246 offset:34816
	ds_read_b128 v[174:177], v246 offset:35840
	ds_read_b128 v[178:181], v246 offset:36864
	ds_read_b128 v[182:185], v246 offset:37888
	ds_read_b128 v[186:189], v246 offset:38912
	ds_read_b128 v[190:193], v246 offset:39936
	global_load_lds_dwordx4 v202, s[8:9]
	v_lshl_add_u64 v[248:249], s[8:9], 0, v[204:205]
	s_mov_b32 m0, s35
	s_nop 0
	global_load_lds_dwordx4 v204, s[8:9]
	s_waitcnt vmcnt(8)
	s_waitcnt lgkmcnt(0)
	s_barrier
	s_setprio 1
	s_waitcnt lgkmcnt(0)
	v_mfma_f32_16x16x32_bf16 v[134:137], v[122:125], v[162:165], v[134:137]
	v_mfma_f32_16x16x32_bf16 v[130:133], v[138:141], v[162:165], v[130:133]
	v_mfma_f32_16x16x32_bf16 v[108:111], v[122:125], v[170:173], v[108:111]
	v_mfma_f32_16x16x32_bf16 v[104:107], v[138:141], v[170:173], v[104:107]
	v_mfma_f32_16x16x32_bf16 v[92:95], v[122:125], v[178:181], v[92:95]
	v_mfma_f32_16x16x32_bf16 v[88:91], v[138:141], v[178:181], v[88:91]
	v_mfma_f32_16x16x32_bf16 v[76:79], v[122:125], v[186:189], v[76:79]
	v_mfma_f32_16x16x32_bf16 v[72:75], v[138:141], v[186:189], v[72:75]
	v_mfma_f32_16x16x32_bf16 v[134:137], v[126:129], v[166:169], v[134:137]
	v_mfma_f32_16x16x32_bf16 v[130:133], v[142:145], v[166:169], v[130:133]
	v_mfma_f32_16x16x32_bf16 v[108:111], v[126:129], v[174:177], v[108:111]
	v_mfma_f32_16x16x32_bf16 v[104:107], v[142:145], v[174:177], v[104:107]
	v_mfma_f32_16x16x32_bf16 v[92:95], v[126:129], v[182:185], v[92:95]
	v_mfma_f32_16x16x32_bf16 v[88:91], v[142:145], v[182:185], v[88:91]
	v_mfma_f32_16x16x32_bf16 v[76:79], v[126:129], v[190:193], v[76:79]
	v_mfma_f32_16x16x32_bf16 v[72:75], v[142:145], v[190:193], v[72:75]
	v_mfma_f32_16x16x32_bf16 v[118:121], v[146:149], v[162:165], v[118:121]
	v_mfma_f32_16x16x32_bf16 v[114:117], v[154:157], v[162:165], v[114:117]
	v_mfma_f32_16x16x32_bf16 v[100:103], v[146:149], v[170:173], v[100:103]
	v_mfma_f32_16x16x32_bf16 v[96:99], v[154:157], v[170:173], v[96:99]
	v_mfma_f32_16x16x32_bf16 v[84:87], v[146:149], v[178:181], v[84:87]
	v_mfma_f32_16x16x32_bf16 v[80:83], v[154:157], v[178:181], v[80:83]
	v_mfma_f32_16x16x32_bf16 v[68:71], v[146:149], v[186:189], v[68:71]
	v_mfma_f32_16x16x32_bf16 v[64:67], v[154:157], v[186:189], v[64:67]
	v_mfma_f32_16x16x32_bf16 v[118:121], v[150:153], v[166:169], v[118:121]
	v_mfma_f32_16x16x32_bf16 v[114:117], v[158:161], v[166:169], v[114:117]
	v_mfma_f32_16x16x32_bf16 v[100:103], v[150:153], v[174:177], v[100:103]
	v_mfma_f32_16x16x32_bf16 v[96:99], v[158:161], v[174:177], v[96:99]
	v_mfma_f32_16x16x32_bf16 v[84:87], v[150:153], v[182:185], v[84:87]
	v_mfma_f32_16x16x32_bf16 v[80:83], v[158:161], v[182:185], v[80:83]
	v_mfma_f32_16x16x32_bf16 v[68:71], v[150:153], v[190:193], v[68:71]
	v_mfma_f32_16x16x32_bf16 v[64:67], v[158:161], v[190:193], v[64:67]
	s_setprio 0
	s_barrier
; #define PG8_MMA(ai, bj, At, Bt) do { __builtin_amdgcn_s_setprio(1); _Pragma("unroll") for (int m = 0; m < 4; ++m) _Pragma("unroll") for (int n = 0; n < 2; ++n) _Pragma("unroll") for (int k = 0; k < 2; ++k) \
;         acc[ai][bj][m][n] = __builtin_amdgcn_mfma_f32_16x16x32_bf16(Bt[n][k], At[m][k], acc[ai][bj][m][n], 0, 0, 0); __builtin_amdgcn_s_setprio(0); } while (0)
; #define PG8_WAIT_V(n) asm volatile("s_waitcnt vmcnt(" #n ")" ::: "memory")
; #define PG8_WAIT_L(n) asm volatile("s_waitcnt lgkmcnt(" #n ")" ::: "memory")
; #define PG8_BAR __builtin_amdgcn_s_barrier()
; #define PG8_SCHED __builtin_amdgcn_sched_barrier(0)
; template <class Epi>
; __device__ __forceinline__ void gemm_phase(LAS unsigned char* lds, const Gemm g, const StaticOrder& S, const Epi& E, const int tid) {
;     ...
;             PG8_WAIT_V(8); PG8_WAIT_L(0); PG8_BAR; PG8_MMA(1, 0, At, B0); PG8_MMA(1, 1, At, B1); PG8_BAR; PG8_SCHED;
;         }
;         if (wr == 0) PG8_BAR;
;     __device__ __forceinline__ void load2(f32x4 (&xv)[2][2][2], const float* rb, int b) const {
; #pragma unroll
;         for (int mm = 0; mm < 2; ++mm) {
;             const float* xp = rb + (size_t)((b >> 1) * HALF + (2 * (b & 1) + mm) * 16) * DM;
; #pragma unroll
;             for (int bj = 0; bj < 2; ++bj) { xv[mm][bj][0] = *(const f32x4*)(xp + bj * HALF); xv[mm][bj][1] = *(const f32x4*)(xp + bj * HALF + 4); }
;         }
;     }
;     __device__ __forceinline__ void operator()(const f32x4 (&acc)[2][2][4][2], const Unit& u, int wr, int wc, int fr_, int fq_, int slot) const {
;         int fr = fr_, fq = fq_; asm volatile("" : "+v"(fr), "+v"(fq));
;         const int pn = u.pn, col0 = pn * BM + wc * 32 + 8 * fq;
;         const float* rb = ((u.pm * BM < MPROMPT) ? R0 : R1) + (size_t)(u.pm * BM + wr * 64 + fr) * DM + col0;
;         f32x4 xa[2][2][2], xb2[2][2][2];
;         load2(xa, rb, 0);
; #pragma unroll
;         for (int b = 0; b < 4; ++b) {
;             if (b + 1 < 4) { if (b & 1) load2(xa, rb, b + 1); else load2(xb2, rb, b + 1); }
	s_add_i32 s8, s13, s11
	s_add_u32 s100, s92, 0x80
	s_addc_u32 s101, s93, 0
	s_mov_b32 m0, s8
	ds_read_b128 v[162:165], v246 offset:49152
	ds_read_b128 v[166:169], v246 offset:50176
	ds_read_b128 v[170:173], v246 offset:51200
	ds_read_b128 v[174:177], v246 offset:52224
	ds_read_b128 v[178:181], v246 offset:53248
	ds_read_b128 v[182:185], v246 offset:54272
	ds_read_b128 v[186:189], v246 offset:55296
	ds_read_b128 v[190:193], v246 offset:56320
	global_load_lds_dwordx4 v112, s[100:101]
	s_add_i32 m0, s8, 0x2000
	s_add_u32 s8, s92, 0x40080
	v_lshl_add_u64 v[210:211], v[212:213], 0, s[24:25]
	s_addc_u32 s9, s93, 0
	s_add_i32 s13, s31, s11
	global_load_lds_dwordx4 v[210:211], off
	s_nop 0
	s_mov_b32 m0, s13
	s_nop 0
	global_load_lds_dwordx4 v112, s[8:9]
	s_nop 0
	s_add_i32 m0, s13, 0x2000
	s_nop 0
	global_load_lds_dwordx4 v200, s[8:9]
	s_add_u32 s100, vcc_lo, 0x80
	s_addc_u32 s101, vcc_hi, 0
	s_mov_b32 m0, s38
	s_nop 0
	global_load_lds_dwordx4 v202, s[100:101]
	s_add_u32 s100, vcc_lo, 0x80
	s_addc_u32 s101, vcc_hi, 0
	s_mov_b32 m0, s39
	s_nop 0
	global_load_lds_dwordx4 v204, s[100:101]
	s_waitcnt vmcnt(8)
	s_waitcnt lgkmcnt(0)
	s_barrier
	s_setprio 1
	s_waitcnt lgkmcnt(0)
	v_mfma_f32_16x16x32_bf16 v[60:63], v[122:125], v[162:165], v[60:63]
	v_mfma_f32_16x16x32_bf16 v[56:59], v[138:141], v[162:165], v[56:59]
	v_mfma_f32_16x16x32_bf16 v[44:47], v[122:125], v[170:173], v[44:47]
	v_mfma_f32_16x16x32_bf16 v[40:43], v[138:141], v[170:173], v[40:43]
	v_mfma_f32_16x16x32_bf16 v[28:31], v[122:125], v[178:181], v[28:31]
	v_mfma_f32_16x16x32_bf16 v[24:27], v[138:141], v[178:181], v[24:27]
	v_mfma_f32_16x16x32_bf16 v[12:15], v[122:125], v[186:189], v[12:15]
	v_mfma_f32_16x16x32_bf16 v[8:11], v[138:141], v[186:189], v[8:11]
	v_mfma_f32_16x16x32_bf16 v[60:63], v[126:129], v[166:169], v[60:63]
	v_mfma_f32_16x16x32_bf16 v[56:59], v[142:145], v[166:169], v[56:59]
	v_mfma_f32_16x16x32_bf16 v[44:47], v[126:129], v[174:177], v[44:47]
	v_mfma_f32_16x16x32_bf16 v[40:43], v[142:145], v[174:177], v[40:43]
	v_mfma_f32_16x16x32_bf16 v[28:31], v[126:129], v[182:185], v[28:31]
	v_mfma_f32_16x16x32_bf16 v[24:27], v[142:145], v[182:185], v[24:27]
	v_mfma_f32_16x16x32_bf16 v[12:15], v[126:129], v[190:193], v[12:15]
	v_mfma_f32_16x16x32_bf16 v[8:11], v[142:145], v[190:193], v[8:11]
	v_mfma_f32_16x16x32_bf16 v[52:55], v[146:149], v[162:165], v[52:55]
	v_mfma_f32_16x16x32_bf16 v[48:51], v[154:157], v[162:165], v[48:51]
	v_mfma_f32_16x16x32_bf16 v[36:39], v[146:149], v[170:173], v[36:39]
	v_mfma_f32_16x16x32_bf16 v[32:35], v[154:157], v[170:173], v[32:35]
	v_mfma_f32_16x16x32_bf16 v[20:23], v[146:149], v[178:181], v[20:23]
	v_mfma_f32_16x16x32_bf16 v[16:19], v[154:157], v[178:181], v[16:19]
	v_mfma_f32_16x16x32_bf16 v[4:7], v[146:149], v[186:189], v[4:7]
	v_mfma_f32_16x16x32_bf16 v[0:3], v[154:157], v[186:189], v[0:3]
	v_mfma_f32_16x16x32_bf16 v[52:55], v[150:153], v[166:169], v[52:55]
	v_mfma_f32_16x16x32_bf16 v[48:51], v[158:161], v[166:169], v[48:51]
	v_mfma_f32_16x16x32_bf16 v[36:39], v[150:153], v[174:177], v[36:39]
	v_mfma_f32_16x16x32_bf16 v[32:35], v[158:161], v[174:177], v[32:35]
	v_mfma_f32_16x16x32_bf16 v[20:23], v[150:153], v[182:185], v[20:23]
	v_mfma_f32_16x16x32_bf16 v[16:19], v[158:161], v[182:185], v[16:19]
	v_mfma_f32_16x16x32_bf16 v[4:7], v[150:153], v[190:193], v[4:7]
	v_mfma_f32_16x16x32_bf16 v[0:3], v[158:161], v[190:193], v[0:3]
	s_setprio 0
	s_barrier
	s_add_i32 s89, s89, 2
	s_add_u32 s45, s45, 0x100
	s_addc_u32 s46, s46, 0
	s_cmp_gt_u32 s89, 13
	s_mov_b64 s[94:95], s[42:43]
	s_cbranch_scc0 .LBB0_160
	s_lshl_b32 s8, s44, 8
	v_mov_b32_e32 v122, v234
	v_mov_b32_e32 v126, v235
	s_or_b32 s8, s8, s23
	s_lshl_b32 s94, s44, 2
	v_lshl_add_u32 v210, v126, 3, s8
	s_lshl_b32 s8, s22, 8
	s_add_i32 s8, s8, s99
	v_add_u32_e32 v212, s8, v122
	v_ashrrev_i32_e32 v213, 31, v212
	v_lshlrev_b64 v[122:123], 12, v[212:213]
	v_lshl_add_u64 v[122:123], s[78:79], 0, v[122:123]
	v_ashrrev_i32_e32 v211, 31, v210
	v_lshl_add_u64 v[214:215], v[210:211], 2, v[122:123]
	s_mov_b64 s[8:9], 0x10000
	v_lshl_add_u64 v[122:123], v[214:215], 0, s[8:9]
	s_mov_b32 s8, 0x10000
	v_add_co_u32_e32 v124, vcc, s8, v214
	s_mov_b64 s[8:9], 0x10200
	s_nop 0
	v_addc_co_u32_e32 v125, vcc, 0, v215, vcc
	global_load_dwordx4 v[186:189], v[214:215], off offset:16
	global_load_dwordx4 v[190:193], v[214:215], off
	global_load_dwordx4 v[178:181], v[214:215], off offset:528
	global_load_dwordx4 v[182:185], v[214:215], off offset:512
	global_load_dwordx4 v[174:177], v[124:125], off
	global_load_dwordx4 v[170:173], v[122:123], off offset:16
	v_lshl_add_u64 v[122:123], v[214:215], 0, s[8:9]
	s_mov_b64 s[8:9], 0x20000
	global_load_dwordx4 v[166:169], v[124:125], off offset:512
	global_load_dwordx4 v[162:165], v[122:123], off offset:16
	v_lshl_add_u64 v[122:123], v[214:215], 0, s[8:9]
	s_mov_b32 s8, 0x20000
	v_add_co_u32_e32 v124, vcc, s8, v214
	s_mov_b64 s[8:9], 0x20200
	s_nop 0
	v_addc_co_u32_e32 v125, vcc, 0, v215, vcc
	global_load_dwordx4 v[158:161], v[124:125], off
	global_load_dwordx4 v[154:157], v[122:123], off offset:16
	v_lshl_add_u64 v[122:123], v[214:215], 0, s[8:9]
	s_mov_b64 s[8:9], 0x30000
	global_load_dwordx4 v[150:153], v[124:125], off offset:512
	global_load_dwordx4 v[146:149], v[122:123], off offset:16
	v_lshl_add_u64 v[122:123], v[214:215], 0, s[8:9]
	s_mov_b32 s8, 0x30000
	v_add_co_u32_e32 v124, vcc, s8, v214
	s_mov_b64 s[8:9], 0x30200
	s_nop 0
	v_addc_co_u32_e32 v125, vcc, 0, v215, vcc
	global_load_dwordx4 v[142:145], v[124:125], off
	global_load_dwordx4 v[138:141], v[122:123], off offset:16
	v_lshl_add_u64 v[122:123], v[214:215], 0, s[8:9]
	v_cmp_eq_u32_e64 s[42:43], 0, v126
	global_load_dwordx4 v[126:129], v[124:125], off offset:512
	s_nop 0
	global_load_dwordx4 v[122:125], v[122:123], off offset:16
	s_and_b64 vcc, exec, s[86:87]
	s_cbranch_vccz .LBB0_163
	s_barrier
; __device__ __forceinline__ u32x4 pack8(f32x4 a, f32x4 b) { u32x4 w; w.x = cvt_pk_bf16(a[0], a[1]); w.y = cvt_pk_bf16(a[2], a[3]); w.z = cvt_pk_bf16(b[0], b[1]); w.w = cvt_pk_bf16(b[2], b[3]); return w; }
; __device__ __forceinline__ float sq4(f32x4 a) { return (a[0] * a[0] + a[1] * a[1]) + (a[2] * a[2] + a[3] * a[3]); }
;     __device__ __forceinline__ void operator()(const f32x4 (&acc)[2][2][4][2], const Unit& u, int wr, int wc, int fr_, int fq_, int slot) const {
;     ...
;             const int ai = b >> 1;
; #pragma unroll
;             for (int mm = 0; mm < 2; ++mm) {
;                 const int m = 2 * (b & 1) + mm;
;                 const int row = u.pm * BM + ai * HALF + wr * 64 + m * 16 + fr;
;                 float* xp = X + (size_t)row * DM + col0; bf16_t* bp = XB + (size_t)row * DM + col0;
;                 float sq = 0.f;
; #pragma unroll
;                 for (int bj = 0; bj < 2; ++bj) {
;                     const f32x4 x0 = ((b & 1) ? xb2[mm][bj][0] : xa[mm][bj][0]) + acc[ai][bj][m][0], x1 = ((b & 1) ? xb2[mm][bj][1] : xa[mm][bj][1]) + acc[ai][bj][m][1];
;                     if (!dry) { *(f32x4*)(xp + bj * HALF) = x0; *(f32x4*)(xp + bj * HALF + 4) = x1;
;                     if (!lastl) *(u32x4*)(bp + bj * HALF) = pack8(x0, x1); }
;                     sq += sq4(x0) + sq4(x1);
;                 }
;                 if (!lastl) { sq = fq_sum(sq); if (fq == 0 && !dry) ss[(size_t)row * 16 + pn * 4 + wc] = sq; }
.LBB0_163:
	s_ashr_i32 s95, s94, 31
	s_mov_b64 s[92:93], -1
	s_andn2_b64 vcc, exec, s[84:85]
	s_waitcnt vmcnt(12)
	v_pk_add_f32 v[190:191], v[134:135], v[190:191]
	v_pk_add_f32 v[134:135], v[130:131], v[186:187]
	v_cndmask_b32_e64 v130, 0, 1, s[84:85]
	v_pk_add_f32 v[192:193], v[136:137], v[192:193]
	v_pk_add_f32 v[136:137], v[132:133], v[188:189]
	v_cmp_ne_u32_e64 s[44:45], 1, v130
	v_pk_add_f32 v[130:131], v[118:119], v[182:183]
	v_pk_add_f32 v[186:187], v[114:115], v[178:179]
	global_store_dwordx4 v[214:215], v[190:193], off
	global_store_dwordx4 v[214:215], v[134:137], off offset:16
	s_cbranch_vccnz .LBB0_167
	v_mul_f32_e32 v118, v191, v191
	v_mul_f32_e32 v119, v193, v193
	v_fmac_f32_e32 v118, v190, v190
	v_fmac_f32_e32 v119, v192, v192
	v_lshlrev_b64 v[114:115], 11, v[212:213]
	v_add_f32_e32 v118, v118, v119
	v_mul_f32_e32 v119, v135, v135
	v_lshl_add_u64 v[114:115], s[6:7], 0, v[114:115]
	v_cvt_pk_bf16_f32 v248, v190, v191
	v_cvt_pk_bf16_f32 v249, v192, v193
	v_cvt_pk_bf16_f32 v250, v134, v135
	v_fmac_f32_e32 v119, v134, v134
	v_mul_f32_e32 v134, v137, v137
	v_lshl_add_u64 v[114:115], v[210:211], 1, v[114:115]
	v_pk_add_f32 v[132:133], v[120:121], v[184:185]
	v_fmac_f32_e32 v134, v136, v136
	v_cvt_pk_bf16_f32 v251, v136, v137
	global_store_dwordx4 v[114:115], v[248:251], off
	v_pk_add_f32 v[188:189], v[116:117], v[180:181]
	global_store_dwordx4 v[214:215], v[130:133], off offset:512
	global_store_dwordx4 v[214:215], v[186:189], off offset:528
	v_add_f32_e32 v119, v119, v134
	v_cvt_pk_bf16_f32 v134, v130, v131
	v_cvt_pk_bf16_f32 v135, v132, v133
	v_cvt_pk_bf16_f32 v136, v186, v187
	v_cvt_pk_bf16_f32 v137, v188, v189
	global_store_dwordx4 v[114:115], v[134:137], off offset:256
	v_mul_f32_e32 v114, v131, v131
	v_mul_f32_e32 v115, v133, v133
	v_fmac_f32_e32 v114, v130, v130
	v_fmac_f32_e32 v115, v132, v132
	v_add_f32_e32 v118, v118, v119
	v_add_f32_e32 v114, v114, v115
	v_mul_f32_e32 v115, v187, v187
	v_mul_f32_e32 v119, v189, v189
	v_fmac_f32_e32 v115, v186, v186
	v_fmac_f32_e32 v119, v188, v188
	v_add_f32_e32 v115, v115, v119
	v_add_f32_e32 v114, v114, v115
	v_add_f32_e32 v114, v118, v114
	v_mov_b32_e32 v115, v114
	s_nop 1
	v_permlane16_swap_b32_e32 v114, v115
	v_add_f32_e32 v114, v114, v115
	v_mov_b32_e32 v115, v114
	s_nop 1
	v_permlane32_swap_b32_e32 v114, v115
	s_and_saveexec_b64 s[92:93], s[42:43]
	s_cbranch_execz .LBB0_166
	v_lshlrev_b64 v[118:119], 6, v[212:213]
	v_lshl_add_u64 v[118:119], s[96:97], 0, v[118:119]
	v_lshl_add_u64 v[118:119], s[94:95], 2, v[118:119]
	s_lshl_b32 s46, s98, 2
	v_lshl_add_u64 v[118:119], v[118:119], 0, s[46:47]
	v_add_f32_e32 v114, v114, v115
	global_store_dword v[118:119], v114, off

; #define PG8_STAGE(bufoff, gbase, voff) do { _Pragma("unroll") for (int _i = 0; _i < 2; ++_i) \
;         __builtin_amdgcn_global_load_lds((const unsigned*)((const char*)(gbase) + (voff)[_i]), (LAS unsigned*)(lds + (bufoff) + ldsw + _i * 8192), 16, 0, 0); } while (0)
; #define PG8_LDA(dst, b, h) do { _Pragma("unroll") for (int m = 0; m < 4; ++m) _Pragma("unroll") for (int k = 0; k < 2; ++k) dst[m][k] = *(const LAS bf16x8*)(lds + PG8_SA(b, h) + aoff + m * 2048 + k * 1024); } while (0)
; #define PG8_LDB(dst, b, h) do { _Pragma("unroll") for (int n = 0; n < 2; ++n) _Pragma("unroll") for (int k = 0; k < 2; ++k) dst[n][k] = *(const LAS bf16x8*)(lds + PG8_SB(b, h) + boff + n * 2048 + k * 1024); } while (0)
; #define PG8_MMA(ai, bj, At, Bt) do { __builtin_amdgcn_s_setprio(1); _Pragma("unroll") for (int m = 0; m < 4; ++m) _Pragma("unroll") for (int n = 0; n < 2; ++n) _Pragma("unroll") for (int k = 0; k < 2; ++k) \
;         acc[ai][bj][m][n] = __builtin_amdgcn_mfma_f32_16x16x32_bf16(Bt[n][k], At[m][k], acc[ai][bj][m][n], 0, 0, 0); __builtin_amdgcn_s_setprio(0); } while (0)
; #define PG8_WAIT_V(n) asm volatile("s_waitcnt vmcnt(" #n ")" ::: "memory")
; #define PG8_WAIT_L(n) asm volatile("s_waitcnt lgkmcnt(" #n ")" ::: "memory")
; #define PG8_BAR __builtin_amdgcn_s_barrier()
; template <class Epi>
; __device__ __forceinline__ void gemm_phase(LAS unsigned char* lds, const Gemm g, const StaticOrder& S, const Epi& E, const int tid) {
;     ...
;         for (int t = 0; t < nt; t += 2) {
;             const bool last = (t == nt - 2);
;             const char* a1 = cA + (size_t)(t + 1) * kstep + ((t + 1) >= 8 ? xtra : 0);
;             const char* a2 = last ? nA : cA + (size_t)(t + 2) * kstep + ((t + 2) >= 8 ? xtra : 0); const char* b2 = last ? nB : cB + (size_t)(t + 2) * kstep;
;             const char* a3 = a2 + kstep; const char* b3 = b2 + kstep;
;             PG8_LDB(B0, 0, 0); PG8_LDB(B1, 0, 1); PG8_SCHED; PG8_LDA(At, 0, 0); PG8_STAGE(PG8_SA(1, 1), a1 + hstepA, voffA);
;             PG8_WAIT_V(8); PG8_WAIT_L(0); PG8_BAR; PG8_MMA(0, 0, At, B0); PG8_MMA(0, 1, At, B1); PG8_BAR; PG8_SCHED;
;             PG8_LDA(At, 0, 1); PG8_STAGE(PG8_SB(0, 0), b2, voffB); PG8_STAGE(PG8_SB(0, 1), b2 + hstepB, voffB); PG8_STAGE(PG8_SA(0, 0), a2, voffA);
;             PG8_WAIT_V(8); PG8_WAIT_L(0); PG8_BAR; PG8_MMA(1, 0, At, B0); PG8_MMA(1, 1, At, B1); PG8_BAR; PG8_SCHED;
.LBB0_230:
	s_add_i32 s96, s40, 2
	s_cmp_gt_u32 s96, 7
	s_cselect_b32 s46, 0x600, 0
	s_cmp_gt_u32 s96, 5
	s_cselect_b32 s8, 0x600, 0
	s_add_u32 s8, s88, s8
	s_addc_u32 s9, s89, 0
	s_add_u32 s8, s8, 0x100
	s_addc_u32 s9, s9, 0
	s_add_i32 s13, 0, 0x10000
	v_add_u32_e32 v142, s13, v210
	v_add_u32_e32 v158, s15, v210
	ds_read_b128 v[130:133], v142
	ds_read_b128 v[134:137], v142 offset:1024
	ds_read_b128 v[138:141], v142 offset:2048
	ds_read_b128 v[142:145], v142 offset:3072
	ds_read_b128 v[146:149], v158
	ds_read_b128 v[150:153], v158 offset:1024
	ds_read_b128 v[154:157], v158 offset:2048
	ds_read_b128 v[158:161], v158 offset:3072
	s_cmp_eq_u32 s40, 12
	s_cselect_b32 s40, s87, vcc_lo
	s_cselect_b32 s91, s83, s9
	s_cselect_b32 s90, s82, s8
	s_cselect_b32 s41, s81, vcc_hi
	v_lshl_add_u64 v[212:213], s[88:89], 0, v[190:191]
	v_lshl_add_u64 v[212:213], v[212:213], 0, s[46:47]
	s_add_i32 m0, s19, 0xc000
	ds_read_b128 v[162:165], v211
	ds_read_b128 v[166:169], v211 offset:1024
	ds_read_b128 v[170:173], v211 offset:2048
	ds_read_b128 v[174:177], v211 offset:3072
	ds_read_b128 v[178:181], v211 offset:4096
	ds_read_b128 v[182:185], v211 offset:5120
	ds_read_b128 v[202:205], v211 offset:6144
	ds_read_b128 v[206:209], v211 offset:7168
	global_load_lds_dwordx4 v[212:213], off
	v_lshl_add_u64 v[212:213], s[88:89], 0, v[192:193]
	v_lshl_add_u64 v[212:213], v[212:213], 0, s[46:47]
	s_add_i32 m0, s19, 0xe000
	s_nop 0
	global_load_lds_dwordx4 v[212:213], off
	s_waitcnt vmcnt(8)
	s_waitcnt lgkmcnt(0)
	s_barrier
	s_setprio 1
	s_waitcnt lgkmcnt(0)
	v_mfma_f32_16x16x32_bf16 v[126:129], v[130:133], v[162:165], v[126:129]
	v_mfma_f32_16x16x32_bf16 v[122:125], v[138:141], v[162:165], v[122:125]
	v_mfma_f32_16x16x32_bf16 v[108:111], v[130:133], v[170:173], v[108:111]
	v_mfma_f32_16x16x32_bf16 v[104:107], v[138:141], v[170:173], v[104:107]
	v_mfma_f32_16x16x32_bf16 v[92:95], v[130:133], v[178:181], v[92:95]
	v_mfma_f32_16x16x32_bf16 v[88:91], v[138:141], v[178:181], v[88:91]
	v_mfma_f32_16x16x32_bf16 v[76:79], v[130:133], v[202:205], v[76:79]
	v_mfma_f32_16x16x32_bf16 v[72:75], v[138:141], v[202:205], v[72:75]
	v_mfma_f32_16x16x32_bf16 v[126:129], v[134:137], v[166:169], v[126:129]
	v_mfma_f32_16x16x32_bf16 v[122:125], v[142:145], v[166:169], v[122:125]
	v_mfma_f32_16x16x32_bf16 v[108:111], v[134:137], v[174:177], v[108:111]
	v_mfma_f32_16x16x32_bf16 v[104:107], v[142:145], v[174:177], v[104:107]
	v_mfma_f32_16x16x32_bf16 v[92:95], v[134:137], v[182:185], v[92:95]
	v_mfma_f32_16x16x32_bf16 v[88:91], v[142:145], v[182:185], v[88:91]
	v_mfma_f32_16x16x32_bf16 v[76:79], v[134:137], v[206:209], v[76:79]
	v_mfma_f32_16x16x32_bf16 v[72:75], v[142:145], v[206:209], v[72:75]
	v_mfma_f32_16x16x32_bf16 v[118:121], v[146:149], v[162:165], v[118:121]
	v_mfma_f32_16x16x32_bf16 v[114:117], v[154:157], v[162:165], v[114:117]
	v_mfma_f32_16x16x32_bf16 v[100:103], v[146:149], v[170:173], v[100:103]
	v_mfma_f32_16x16x32_bf16 v[96:99], v[154:157], v[170:173], v[96:99]
	v_mfma_f32_16x16x32_bf16 v[84:87], v[146:149], v[178:181], v[84:87]
	v_mfma_f32_16x16x32_bf16 v[80:83], v[154:157], v[178:181], v[80:83]
	v_mfma_f32_16x16x32_bf16 v[68:71], v[146:149], v[202:205], v[68:71]
	v_mfma_f32_16x16x32_bf16 v[64:67], v[154:157], v[202:205], v[64:67]
	v_mfma_f32_16x16x32_bf16 v[118:121], v[150:153], v[166:169], v[118:121]
	v_mfma_f32_16x16x32_bf16 v[114:117], v[158:161], v[166:169], v[114:117]
	v_mfma_f32_16x16x32_bf16 v[100:103], v[150:153], v[174:177], v[100:103]
	v_mfma_f32_16x16x32_bf16 v[96:99], v[158:161], v[174:177], v[96:99]
	v_mfma_f32_16x16x32_bf16 v[84:87], v[150:153], v[182:185], v[84:87]
	v_mfma_f32_16x16x32_bf16 v[80:83], v[158:161], v[182:185], v[80:83]
	v_mfma_f32_16x16x32_bf16 v[68:71], v[150:153], v[206:209], v[68:71]
	v_mfma_f32_16x16x32_bf16 v[64:67], v[158:161], v[206:209], v[64:67]
	s_setprio 0
	s_barrier
	s_add_i32 s8, s13, s11
	v_lshl_add_u64 v[212:213], s[40:41], 0, v[112:113]
	s_mov_b32 m0, s8
	ds_read_b128 v[162:165], v211 offset:16384
	ds_read_b128 v[166:169], v211 offset:17408
	ds_read_b128 v[170:173], v211 offset:18432
	ds_read_b128 v[174:177], v211 offset:19456
	ds_read_b128 v[178:181], v211 offset:20480
	ds_read_b128 v[182:185], v211 offset:21504
	ds_read_b128 v[202:205], v211 offset:22528
	ds_read_b128 v[206:209], v211 offset:23552
	global_load_lds_dwordx4 v112, s[40:41]
	s_add_i32 m0, s8, 0x2000
	s_add_u32 s8, s40, 0x40000
	v_lshl_add_u64 v[214:215], s[40:41], 0, v[200:201]
	s_addc_u32 s9, s41, 0
	s_add_i32 s13, s15, s11
	global_load_lds_dwordx4 v200, s[40:41]
	s_nop 0
	s_mov_b32 m0, s13
	v_lshl_add_u64 v[236:237], s[90:91], 0, v[188:189]
	global_load_lds_dwordx4 v112, s[8:9]
	s_nop 0
	s_add_i32 m0, s13, 0x2000
	s_nop 0
	global_load_lds_dwordx4 v200, s[8:9]
	s_nop 0
	s_mov_b32 m0, s19
	s_nop 0
	global_load_lds_dwordx4 v186, s[90:91]
	s_mov_b32 m0, s23
	s_nop 0
	global_load_lds_dwordx4 v188, s[90:91]
	s_waitcnt vmcnt(8)
	s_waitcnt lgkmcnt(0)
	s_barrier
; #define PG8_STAGE(bufoff, gbase, voff) do { _Pragma("unroll") for (int _i = 0; _i < 2; ++_i) \
;         __builtin_amdgcn_global_load_lds((const unsigned*)((const char*)(gbase) + (voff)[_i]), (LAS unsigned*)(lds + (bufoff) + ldsw + _i * 8192), 16, 0, 0); } while (0)
; #define PG8_LDA(dst, b, h) do { _Pragma("unroll") for (int m = 0; m < 4; ++m) _Pragma("unroll") for (int k = 0; k < 2; ++k) dst[m][k] = *(const LAS bf16x8*)(lds + PG8_SA(b, h) + aoff + m * 2048 + k * 1024); } while (0)
; #define PG8_LDB(dst, b, h) do { _Pragma("unroll") for (int n = 0; n < 2; ++n) _Pragma("unroll") for (int k = 0; k < 2; ++k) dst[n][k] = *(const LAS bf16x8*)(lds + PG8_SB(b, h) + boff + n * 2048 + k * 1024); } while (0)
; #define PG8_MMA(ai, bj, At, Bt) do { __builtin_amdgcn_s_setprio(1); _Pragma("unroll") for (int m = 0; m < 4; ++m) _Pragma("unroll") for (int n = 0; n < 2; ++n) _Pragma("unroll") for (int k = 0; k < 2; ++k) \
;         acc[ai][bj][m][n] = __builtin_amdgcn_mfma_f32_16x16x32_bf16(Bt[n][k], At[m][k], acc[ai][bj][m][n], 0, 0, 0); __builtin_amdgcn_s_setprio(0); } while (0)
; #define PG8_WAIT_V(n) asm volatile("s_waitcnt vmcnt(" #n ")" ::: "memory")
; #define PG8_WAIT_L(n) asm volatile("s_waitcnt lgkmcnt(" #n ")" ::: "memory")
; #define PG8_BAR __builtin_amdgcn_s_barrier()
; #define PG8_SCHED __builtin_amdgcn_sched_barrier(0)
; template <class Epi>
; __device__ __forceinline__ void gemm_phase(LAS unsigned char* lds, const Gemm g, const StaticOrder& S, const Epi& E, const int tid) {
;     ...
;             PG8_WAIT_V(8); PG8_WAIT_L(0); PG8_BAR; PG8_MMA(0, 0, At, B0); PG8_MMA(0, 1, At, B1); PG8_BAR; PG8_SCHED;
;             PG8_LDA(At, 0, 1); PG8_STAGE(PG8_SB(0, 0), b2, voffB); PG8_STAGE(PG8_SB(0, 1), b2 + hstepB, voffB); PG8_STAGE(PG8_SA(0, 0), a2, voffA);
;             PG8_WAIT_V(8); PG8_WAIT_L(0); PG8_BAR; PG8_MMA(1, 0, At, B0); PG8_MMA(1, 1, At, B1); PG8_BAR; PG8_SCHED;
;             PG8_LDB(B0, 1, 0); PG8_LDB(B1, 1, 1); PG8_SCHED; PG8_LDA(At, 1, 0); PG8_STAGE(PG8_SA(0, 1), a2 + hstepA, voffA);
;             PG8_WAIT_V(8); PG8_WAIT_L(0); PG8_BAR; PG8_MMA(0, 0, At, B0); PG8_MMA(0, 1, At, B1); PG8_BAR; PG8_SCHED;
;             PG8_LDA(At, 1, 1); PG8_STAGE(PG8_SB(1, 0), b3, voffB); PG8_STAGE(PG8_SB(1, 1), b3 + hstepB, voffB); PG8_STAGE(PG8_SA(1, 0), a3, voffA);
	s_setprio 1
	s_waitcnt lgkmcnt(0)
	v_mfma_f32_16x16x32_bf16 v[60:63], v[130:133], v[162:165], v[60:63]
	v_mfma_f32_16x16x32_bf16 v[56:59], v[138:141], v[162:165], v[56:59]
	v_mfma_f32_16x16x32_bf16 v[44:47], v[130:133], v[170:173], v[44:47]
	v_mfma_f32_16x16x32_bf16 v[40:43], v[138:141], v[170:173], v[40:43]
	v_mfma_f32_16x16x32_bf16 v[28:31], v[130:133], v[178:181], v[28:31]
	v_mfma_f32_16x16x32_bf16 v[24:27], v[138:141], v[178:181], v[24:27]
	v_mfma_f32_16x16x32_bf16 v[12:15], v[130:133], v[202:205], v[12:15]
	v_mfma_f32_16x16x32_bf16 v[8:11], v[138:141], v[202:205], v[8:11]
	v_mfma_f32_16x16x32_bf16 v[60:63], v[134:137], v[166:169], v[60:63]
	v_mfma_f32_16x16x32_bf16 v[56:59], v[142:145], v[166:169], v[56:59]
	v_mfma_f32_16x16x32_bf16 v[44:47], v[134:137], v[174:177], v[44:47]
	v_mfma_f32_16x16x32_bf16 v[40:43], v[142:145], v[174:177], v[40:43]
	v_mfma_f32_16x16x32_bf16 v[28:31], v[134:137], v[182:185], v[28:31]
	v_mfma_f32_16x16x32_bf16 v[24:27], v[142:145], v[182:185], v[24:27]
	v_mfma_f32_16x16x32_bf16 v[12:15], v[134:137], v[206:209], v[12:15]
	v_mfma_f32_16x16x32_bf16 v[8:11], v[142:145], v[206:209], v[8:11]
	v_mfma_f32_16x16x32_bf16 v[52:55], v[146:149], v[162:165], v[52:55]
	v_mfma_f32_16x16x32_bf16 v[48:51], v[154:157], v[162:165], v[48:51]
	v_mfma_f32_16x16x32_bf16 v[36:39], v[146:149], v[170:173], v[36:39]
	v_mfma_f32_16x16x32_bf16 v[32:35], v[154:157], v[170:173], v[32:35]
	v_mfma_f32_16x16x32_bf16 v[20:23], v[146:149], v[178:181], v[20:23]
	v_mfma_f32_16x16x32_bf16 v[16:19], v[154:157], v[178:181], v[16:19]
	v_mfma_f32_16x16x32_bf16 v[4:7], v[146:149], v[202:205], v[4:7]
	v_mfma_f32_16x16x32_bf16 v[0:3], v[154:157], v[202:205], v[0:3]
	v_mfma_f32_16x16x32_bf16 v[52:55], v[150:153], v[166:169], v[52:55]
	v_mfma_f32_16x16x32_bf16 v[48:51], v[158:161], v[166:169], v[48:51]
	v_mfma_f32_16x16x32_bf16 v[36:39], v[150:153], v[174:177], v[36:39]
	v_mfma_f32_16x16x32_bf16 v[32:35], v[158:161], v[174:177], v[32:35]
	v_mfma_f32_16x16x32_bf16 v[20:23], v[150:153], v[182:185], v[20:23]
	v_mfma_f32_16x16x32_bf16 v[16:19], v[158:161], v[182:185], v[16:19]
	v_mfma_f32_16x16x32_bf16 v[4:7], v[150:153], v[206:209], v[4:7]
	v_mfma_f32_16x16x32_bf16 v[0:3], v[158:161], v[206:209], v[0:3]
	s_setprio 0
	s_barrier
	s_add_i32 s13, 0, 0x18000
	s_add_i32 s31, 0, 0x1c000
	v_add_u32_e32 v142, s13, v210
	v_add_u32_e32 v158, s31, v210
	ds_read_b128 v[130:133], v142
	ds_read_b128 v[134:137], v142 offset:1024
	ds_read_b128 v[138:141], v142 offset:2048
	ds_read_b128 v[142:145], v142 offset:3072
	ds_read_b128 v[146:149], v158
	ds_read_b128 v[150:153], v158 offset:1024
	ds_read_b128 v[154:157], v158 offset:2048
	ds_read_b128 v[158:161], v158 offset:3072
	s_add_u32 s8, s90, 0x90000
	s_addc_u32 s9, s91, 0
	s_mov_b32 m0, s28
	s_nop 0
	ds_read_b128 v[162:165], v211 offset:32768
	ds_read_b128 v[166:169], v211 offset:33792
	ds_read_b128 v[170:173], v211 offset:34816
	ds_read_b128 v[174:177], v211 offset:35840
	ds_read_b128 v[178:181], v211 offset:36864
	ds_read_b128 v[182:185], v211 offset:37888
	ds_read_b128 v[202:205], v211 offset:38912
	ds_read_b128 v[206:209], v211 offset:39936
	global_load_lds_dwordx4 v186, s[8:9]
	v_lshl_add_u64 v[238:239], s[8:9], 0, v[188:189]
	s_mov_b32 m0, s30
	s_nop 0
	global_load_lds_dwordx4 v188, s[8:9]
	s_waitcnt vmcnt(8)
	s_waitcnt lgkmcnt(0)
	s_barrier
	s_setprio 1
	s_waitcnt lgkmcnt(0)
	v_mfma_f32_16x16x32_bf16 v[126:129], v[130:133], v[162:165], v[126:129]
	v_mfma_f32_16x16x32_bf16 v[122:125], v[138:141], v[162:165], v[122:125]
	v_mfma_f32_16x16x32_bf16 v[108:111], v[130:133], v[170:173], v[108:111]
	v_mfma_f32_16x16x32_bf16 v[104:107], v[138:141], v[170:173], v[104:107]
	v_mfma_f32_16x16x32_bf16 v[92:95], v[130:133], v[178:181], v[92:95]
	v_mfma_f32_16x16x32_bf16 v[88:91], v[138:141], v[178:181], v[88:91]
	v_mfma_f32_16x16x32_bf16 v[76:79], v[130:133], v[202:205], v[76:79]
	v_mfma_f32_16x16x32_bf16 v[72:75], v[138:141], v[202:205], v[72:75]
	v_mfma_f32_16x16x32_bf16 v[126:129], v[134:137], v[166:169], v[126:129]
	v_mfma_f32_16x16x32_bf16 v[122:125], v[142:145], v[166:169], v[122:125]
	v_mfma_f32_16x16x32_bf16 v[108:111], v[134:137], v[174:177], v[108:111]
	v_mfma_f32_16x16x32_bf16 v[104:107], v[142:145], v[174:177], v[104:107]
	v_mfma_f32_16x16x32_bf16 v[92:95], v[134:137], v[182:185], v[92:95]
	v_mfma_f32_16x16x32_bf16 v[88:91], v[142:145], v[182:185], v[88:91]
	v_mfma_f32_16x16x32_bf16 v[76:79], v[134:137], v[206:209], v[76:79]
	v_mfma_f32_16x16x32_bf16 v[72:75], v[142:145], v[206:209], v[72:75]
	v_mfma_f32_16x16x32_bf16 v[118:121], v[146:149], v[162:165], v[118:121]
	v_mfma_f32_16x16x32_bf16 v[114:117], v[154:157], v[162:165], v[114:117]
	v_mfma_f32_16x16x32_bf16 v[100:103], v[146:149], v[170:173], v[100:103]
	v_mfma_f32_16x16x32_bf16 v[96:99], v[154:157], v[170:173], v[96:99]
	v_mfma_f32_16x16x32_bf16 v[84:87], v[146:149], v[178:181], v[84:87]
	v_mfma_f32_16x16x32_bf16 v[80:83], v[154:157], v[178:181], v[80:83]
	v_mfma_f32_16x16x32_bf16 v[68:71], v[146:149], v[202:205], v[68:71]
	v_mfma_f32_16x16x32_bf16 v[64:67], v[154:157], v[202:205], v[64:67]
	v_mfma_f32_16x16x32_bf16 v[118:121], v[150:153], v[166:169], v[118:121]
	v_mfma_f32_16x16x32_bf16 v[114:117], v[158:161], v[166:169], v[114:117]
	v_mfma_f32_16x16x32_bf16 v[100:103], v[150:153], v[174:177], v[100:103]
	v_mfma_f32_16x16x32_bf16 v[96:99], v[158:161], v[174:177], v[96:99]
	v_mfma_f32_16x16x32_bf16 v[84:87], v[150:153], v[182:185], v[84:87]
	v_mfma_f32_16x16x32_bf16 v[80:83], v[158:161], v[182:185], v[80:83]
	v_mfma_f32_16x16x32_bf16 v[68:71], v[150:153], v[206:209], v[68:71]
	v_mfma_f32_16x16x32_bf16 v[64:67], v[158:161], v[206:209], v[64:67]
	s_setprio 0
	s_barrier
; #define PG8_MMA(ai, bj, At, Bt) do { __builtin_amdgcn_s_setprio(1); _Pragma("unroll") for (int m = 0; m < 4; ++m) _Pragma("unroll") for (int n = 0; n < 2; ++n) _Pragma("unroll") for (int k = 0; k < 2; ++k) \
;         acc[ai][bj][m][n] = __builtin_amdgcn_mfma_f32_16x16x32_bf16(Bt[n][k], At[m][k], acc[ai][bj][m][n], 0, 0, 0); __builtin_amdgcn_s_setprio(0); } while (0)
; #define PG8_WAIT_V(n) asm volatile("s_waitcnt vmcnt(" #n ")" ::: "memory")
; #define PG8_WAIT_L(n) asm volatile("s_waitcnt lgkmcnt(" #n ")" ::: "memory")
; #define PG8_BAR __builtin_amdgcn_s_barrier()
; #define PG8_SCHED __builtin_amdgcn_sched_barrier(0)
; template <class Epi>
; __device__ __forceinline__ void gemm_phase(LAS unsigned char* lds, const Gemm g, const StaticOrder& S, const Epi& E, const int tid) {
;     ...
;             PG8_WAIT_V(8); PG8_WAIT_L(0); PG8_BAR; PG8_MMA(1, 0, At, B0); PG8_MMA(1, 1, At, B1); PG8_BAR; PG8_SCHED;
;         }
;         if (wr == 0) PG8_BAR;
;     __device__ __forceinline__ void load2(f32x4 (&xv)[2][2][2], const float* rb, int b) const {
; #pragma unroll
;         for (int mm = 0; mm < 2; ++mm) {
;             const float* xp = rb + (size_t)((b >> 1) * HALF + (2 * (b & 1) + mm) * 16) * DM;
; #pragma unroll
;             for (int bj = 0; bj < 2; ++bj) { xv[mm][bj][0] = *(const f32x4*)(xp + bj * HALF); xv[mm][bj][1] = *(const f32x4*)(xp + bj * HALF + 4); }
;         }
;     }
;     __device__ __forceinline__ void operator()(const f32x4 (&acc)[2][2][4][2], const Unit& u, int wr, int wc, int fr_, int fq_, int slot) const {
;         int fr = fr_, fq = fq_; asm volatile("" : "+v"(fr), "+v"(fq));
;         const int pn = u.pn, col0 = pn * BM + wc * 32 + 8 * fq;
;         const float* rb = ((u.pm * BM < MPROMPT) ? R0 : R1) + (size_t)(u.pm * BM + wr * 64 + fr) * DM + col0;
;         f32x4 xa[2][2][2], xb2[2][2][2];
;         load2(xa, rb, 0);
; #pragma unroll
;         for (int b = 0; b < 4; ++b) {
;             if (b + 1 < 4) { if (b & 1) load2(xa, rb, b + 1); else load2(xb2, rb, b + 1); }
	s_add_i32 s8, s13, s11
	s_add_u32 s100, s40, 0x80
	s_addc_u32 s101, s41, 0
	s_mov_b32 m0, s8
	ds_read_b128 v[162:165], v211 offset:49152
	ds_read_b128 v[166:169], v211 offset:50176
	ds_read_b128 v[170:173], v211 offset:51200
	ds_read_b128 v[174:177], v211 offset:52224
	ds_read_b128 v[178:181], v211 offset:53248
	ds_read_b128 v[182:185], v211 offset:54272
	ds_read_b128 v[202:205], v211 offset:55296
	ds_read_b128 v[206:209], v211 offset:56320
	global_load_lds_dwordx4 v112, s[100:101]
	s_add_i32 m0, s8, 0x2000
	s_add_u32 s8, s40, 0x40080
	v_lshl_add_u64 v[212:213], v[214:215], 0, s[24:25]
	s_addc_u32 s9, s41, 0
	s_add_i32 s13, s31, s11
	global_load_lds_dwordx4 v[212:213], off
	s_nop 0
	s_mov_b32 m0, s13
	s_nop 0
	global_load_lds_dwordx4 v112, s[8:9]
	s_nop 0
	s_add_i32 m0, s13, 0x2000
	s_nop 0
	global_load_lds_dwordx4 v200, s[8:9]
	s_add_u32 s100, s90, 0x80
	s_addc_u32 s101, s91, 0
	s_mov_b32 m0, s99
	s_nop 0
	global_load_lds_dwordx4 v186, s[100:101]
	s_add_u32 s100, s90, 0x80
	s_addc_u32 s101, s91, 0
	s_mov_b32 m0, s33
	s_nop 0
	global_load_lds_dwordx4 v188, s[100:101]
	s_waitcnt vmcnt(8)
	s_waitcnt lgkmcnt(0)
	s_barrier
	s_setprio 1
	s_waitcnt lgkmcnt(0)
	v_mfma_f32_16x16x32_bf16 v[60:63], v[130:133], v[162:165], v[60:63]
	v_mfma_f32_16x16x32_bf16 v[56:59], v[138:141], v[162:165], v[56:59]
	v_mfma_f32_16x16x32_bf16 v[44:47], v[130:133], v[170:173], v[44:47]
	v_mfma_f32_16x16x32_bf16 v[40:43], v[138:141], v[170:173], v[40:43]
	v_mfma_f32_16x16x32_bf16 v[28:31], v[130:133], v[178:181], v[28:31]
	v_mfma_f32_16x16x32_bf16 v[24:27], v[138:141], v[178:181], v[24:27]
	v_mfma_f32_16x16x32_bf16 v[12:15], v[130:133], v[202:205], v[12:15]
	v_mfma_f32_16x16x32_bf16 v[8:11], v[138:141], v[202:205], v[8:11]
	v_mfma_f32_16x16x32_bf16 v[60:63], v[134:137], v[166:169], v[60:63]
	v_mfma_f32_16x16x32_bf16 v[56:59], v[142:145], v[166:169], v[56:59]
	v_mfma_f32_16x16x32_bf16 v[44:47], v[134:137], v[174:177], v[44:47]
	v_mfma_f32_16x16x32_bf16 v[40:43], v[142:145], v[174:177], v[40:43]
	v_mfma_f32_16x16x32_bf16 v[28:31], v[134:137], v[182:185], v[28:31]
	v_mfma_f32_16x16x32_bf16 v[24:27], v[142:145], v[182:185], v[24:27]
	v_mfma_f32_16x16x32_bf16 v[12:15], v[134:137], v[206:209], v[12:15]
	v_mfma_f32_16x16x32_bf16 v[8:11], v[142:145], v[206:209], v[8:11]
	v_mfma_f32_16x16x32_bf16 v[52:55], v[146:149], v[162:165], v[52:55]
	v_mfma_f32_16x16x32_bf16 v[48:51], v[154:157], v[162:165], v[48:51]
	v_mfma_f32_16x16x32_bf16 v[36:39], v[146:149], v[170:173], v[36:39]
	v_mfma_f32_16x16x32_bf16 v[32:35], v[154:157], v[170:173], v[32:35]
	v_mfma_f32_16x16x32_bf16 v[20:23], v[146:149], v[178:181], v[20:23]
	v_mfma_f32_16x16x32_bf16 v[16:19], v[154:157], v[178:181], v[16:19]
	v_mfma_f32_16x16x32_bf16 v[4:7], v[146:149], v[202:205], v[4:7]
	v_mfma_f32_16x16x32_bf16 v[0:3], v[154:157], v[202:205], v[0:3]
	v_mfma_f32_16x16x32_bf16 v[52:55], v[150:153], v[166:169], v[52:55]
	v_mfma_f32_16x16x32_bf16 v[48:51], v[158:161], v[166:169], v[48:51]
	v_mfma_f32_16x16x32_bf16 v[36:39], v[150:153], v[174:177], v[36:39]
	v_mfma_f32_16x16x32_bf16 v[32:35], v[158:161], v[174:177], v[32:35]
	v_mfma_f32_16x16x32_bf16 v[20:23], v[150:153], v[182:185], v[20:23]
	v_mfma_f32_16x16x32_bf16 v[16:19], v[158:161], v[182:185], v[16:19]
	v_mfma_f32_16x16x32_bf16 v[4:7], v[150:153], v[206:209], v[4:7]
	v_mfma_f32_16x16x32_bf16 v[0:3], v[158:161], v[206:209], v[0:3]
	s_setprio 0
	s_barrier
	s_add_u32 s88, s88, 0x100
	s_addc_u32 s89, s89, 0
	s_add_u32 vcc_lo, vcc_lo, 0x100
	s_addc_u32 vcc_hi, vcc_hi, 0
	s_cmp_gt_u32 s96, 13
	s_mov_b32 s40, s96
	s_cbranch_scc0 .LBB0_230
	s_lshl_b32 s8, s86, 8
	s_or_b32 s8, s8, s93
	v_mov_b32_e32 v246, v235
	v_mov_b32_e32 v130, v234
	s_cmpk_lt_i32 s37, 0x80
	s_cselect_b32 s9, s57, s95
	v_lshl_add_u32 v202, v246, 3, s8
	s_cselect_b32 s8, s94, s98
	s_lshl_b32 s13, s37, 8
	s_add_i32 s13, s13, s92
	v_add_u32_e32 v204, s13, v130
	v_ashrrev_i32_e32 v205, 31, v204
	v_lshlrev_b64 v[208:209], 12, v[204:205]
	v_ashrrev_i32_e32 v203, 31, v202
	v_lshl_add_u64 v[130:131], s[8:9], 0, v[208:209]
	v_lshlrev_b64 v[228:229], 2, v[202:203]
	v_lshl_add_u64 v[206:207], v[130:131], 0, v[228:229]
	s_mov_b64 s[8:9], 0x10000
	v_lshl_add_u64 v[130:131], v[206:207], 0, s[8:9]
	s_mov_b32 s8, 0x10000
	v_add_co_u32_e32 v132, vcc, s8, v206
	s_mov_b64 s[8:9], 0x10200
	v_lshl_add_u64 v[134:135], v[206:207], 0, s[8:9]
	s_mov_b64 s[8:9], 0x20000
	v_addc_co_u32_e32 v133, vcc, 0, v207, vcc
	v_lshl_add_u64 v[136:137], v[206:207], 0, s[8:9]
	s_mov_b32 s8, 0x20000
	v_add_co_u32_e32 v138, vcc, s8, v206
	s_mov_b64 s[8:9], 0x20200
	global_load_dwordx4 v[212:215], v[206:207], off
	global_load_dwordx4 v[236:239], v[206:207], off offset:16
	global_load_dwordx4 v[182:185], v[206:207], off offset:512
	global_load_dwordx4 v[178:181], v[206:207], off offset:528
	v_lshl_add_u64 v[140:141], v[206:207], 0, s[8:9]
	s_mov_b64 s[8:9], 0x30000
	v_addc_co_u32_e32 v139, vcc, 0, v207, vcc
	v_lshl_add_u64 v[240:241], v[206:207], 0, s[8:9]
	s_mov_b32 s8, 0x30000
	v_add_co_u32_e32 v242, vcc, s8, v206
	s_mov_b64 s[8:9], 0x30200
	s_nop 0
	v_addc_co_u32_e32 v243, vcc, 0, v207, vcc
	v_lshl_add_u64 v[244:245], v[206:207], 0, s[8:9]
	global_load_dwordx4 v[174:177], v[132:133], off
	global_load_dwordx4 v[170:173], v[130:131], off offset:16
	global_load_dwordx4 v[166:169], v[132:133], off offset:512
	global_load_dwordx4 v[162:165], v[134:135], off offset:16
	global_load_dwordx4 v[158:161], v[138:139], off
	global_load_dwordx4 v[154:157], v[136:137], off offset:16
	global_load_dwordx4 v[150:153], v[138:139], off offset:512
	global_load_dwordx4 v[146:149], v[140:141], off offset:16
	global_load_dwordx4 v[142:145], v[242:243], off
	s_nop 0
	global_load_dwordx4 v[138:141], v[240:241], off offset:16
	global_load_dwordx4 v[130:133], v[242:243], off offset:512
	global_load_dwordx4 v[134:137], v[244:245], off offset:16
	s_and_b64 vcc, exec, s[44:45]
	s_cbranch_vccz .LBB0_233
	s_barrier
; __device__ __forceinline__ u32x4 pack8(f32x4 a, f32x4 b) { u32x4 w; w.x = cvt_pk_bf16(a[0], a[1]); w.y = cvt_pk_bf16(a[2], a[3]); w.z = cvt_pk_bf16(b[0], b[1]); w.w = cvt_pk_bf16(b[2], b[3]); return w; }
; __device__ __forceinline__ float sq4(f32x4 a) { return (a[0] * a[0] + a[1] * a[1]) + (a[2] * a[2] + a[3] * a[3]); }
;     __device__ __forceinline__ void operator()(const f32x4 (&acc)[2][2][4][2], const Unit& u, int wr, int wc, int fr_, int fq_, int slot) const {
;     ...
;         const int pn = u.pn, col0 = pn * BM + wc * 32 + 8 * fq;
;         const float* rb = ((u.pm * BM < MPROMPT) ? R0 : R1) + (size_t)(u.pm * BM + wr * 64 + fr) * DM + col0;
;         f32x4 xa[2][2][2], xb2[2][2][2];
;         load2(xa, rb, 0);
; #pragma unroll
;         for (int b = 0; b < 4; ++b) {
;             if (b + 1 < 4) { if (b & 1) load2(xa, rb, b + 1); else load2(xb2, rb, b + 1); }
;             const int ai = b >> 1;
; #pragma unroll
;             for (int mm = 0; mm < 2; ++mm) {
;                 const int m = 2 * (b & 1) + mm;
;                 const int row = u.pm * BM + ai * HALF + wr * 64 + m * 16 + fr;
;                 float* xp = X + (size_t)row * DM + col0; bf16_t* bp = XB + (size_t)row * DM + col0;
;                 float sq = 0.f;
; #pragma unroll
;                 for (int bj = 0; bj < 2; ++bj) {
;                     const f32x4 x0 = ((b & 1) ? xb2[mm][bj][0] : xa[mm][bj][0]) + acc[ai][bj][m][0], x1 = ((b & 1) ? xb2[mm][bj][1] : xa[mm][bj][1]) + acc[ai][bj][m][1];
;                     if (!dry) { *(f32x4*)(xp + bj * HALF) = x0; *(f32x4*)(xp + bj * HALF + 4) = x1;
;                     if (!lastl) *(u32x4*)(bp + bj * HALF) = pack8(x0, x1); }
;                     sq += sq4(x0) + sq4(x1);
;                 }
;                 if (!lastl) { sq = fq_sum(sq); if (fq == 0 && !dry) ss[(size_t)row * 16 + pn * 4 + wc] = sq; }
.LBB0_233:
	v_lshl_add_u64 v[208:209], s[78:79], 0, v[208:209]
	v_lshlrev_b64 v[240:241], 11, v[204:205]
	v_lshl_add_u64 v[228:229], v[208:209], 0, v[228:229]
	v_lshl_add_u64 v[240:241], s[6:7], 0, v[240:241]
	v_lshl_add_u64 v[208:209], v[202:203], 1, v[240:241]
	s_lshl_b32 s86, s86, 2
	v_cmp_eq_u32_e64 s[40:41], 0, v246
	s_ashr_i32 s87, s86, 31
	s_waitcnt vmcnt(12)
	v_pk_add_f32 v[128:129], v[128:129], v[214:215]
	v_pk_add_f32 v[126:127], v[126:127], v[212:213]
	v_pk_add_f32 v[124:125], v[124:125], v[238:239]
	v_pk_add_f32 v[122:123], v[122:123], v[236:237]
	v_pk_add_f32 v[118:119], v[118:119], v[182:183]
	v_pk_add_f32 v[114:115], v[114:115], v[178:179]
	global_store_dwordx4 v[228:229], v[126:129], off
	global_store_dwordx4 v[228:229], v[122:125], off offset:16
	v_cvt_pk_bf16_f32 v178, v126, v127
	v_cvt_pk_bf16_f32 v179, v128, v129
	v_mul_f32_e32 v182, v123, v123
	v_mul_f32_e32 v127, v127, v127
	v_mul_f32_e32 v129, v129, v129
	v_mul_f32_e32 v183, v125, v125
	v_pk_add_f32 v[120:121], v[120:121], v[184:185]
	v_mul_f32_e32 v184, v119, v119
	v_fmac_f32_e32 v127, v126, v126
	v_fmac_f32_e32 v129, v128, v128
	v_fmac_f32_e32 v182, v122, v122
	v_fmac_f32_e32 v183, v124, v124
	v_pk_add_f32 v[116:117], v[116:117], v[180:181]
	v_cvt_pk_bf16_f32 v180, v122, v123
	v_cvt_pk_bf16_f32 v181, v124, v125
	global_store_dwordx4 v[208:209], v[178:181], off
	global_store_dwordx4 v[228:229], v[118:121], off offset:512
	global_store_dwordx4 v[228:229], v[114:117], off offset:528
	v_cvt_pk_bf16_f32 v122, v118, v119
	v_cvt_pk_bf16_f32 v123, v120, v121
	v_cvt_pk_bf16_f32 v124, v114, v115
	v_fmac_f32_e32 v184, v118, v118
	v_add_f32_e32 v118, v127, v129
	v_add_f32_e32 v119, v182, v183
	v_mul_f32_e32 v115, v115, v115
	v_add_f32_e32 v118, v118, v119
	v_mul_f32_e32 v119, v121, v121
	v_fmac_f32_e32 v115, v114, v114
	v_mul_f32_e32 v114, v117, v117
	v_fmac_f32_e32 v119, v120, v120
	v_fmac_f32_e32 v114, v116, v116
	v_add_f32_e32 v119, v184, v119
	v_add_f32_e32 v114, v115, v114
	v_add_f32_e32 v114, v119, v114
	v_add_f32_e32 v114, v118, v114
	v_mov_b32_e32 v115, v114
	s_nop 1
	v_permlane16_swap_b32_e32 v114, v115
	v_add_f32_e32 v114, v114, v115
	v_mov_b32_e32 v115, v114
	s_nop 1
	v_permlane32_swap_b32_e32 v114, v115
	v_cvt_pk_bf16_f32 v125, v116, v117
	global_store_dwordx4 v[208:209], v[122:125], off offset:256
	s_and_saveexec_b64 s[88:89], s[40:41]
	v_readlane_b32 s96, v255, 45
	v_readlane_b32 s97, v255, 46
	s_cbranch_execz .LBB0_235
	v_lshlrev_b64 v[116:117], 6, v[204:205]
	v_lshl_add_u64 v[116:117], s[96:97], 0, v[116:117]
	v_lshl_add_u64 v[116:117], s[86:87], 2, v[116:117]
	s_lshl_b32 s46, s35, 2
	v_lshl_add_u64 v[116:117], v[116:117], 0, s[46:47]
	v_add_f32_e32 v114, v114, v115
	global_store_dword v[116:117], v114, off
